# mLSTM chunk loop: the gate block of the gate-computing wave runs at s_setprio 2 so the lone critical-path wave of that barrier segment wins VALU issue
# baseline (speedup 1.0000x reference)
.LBB0_237:
	s_setprio 2
	s_waitcnt vmcnt(0)
	v_lshlrev_b32_e32 v35, 16, v35
	v_lshlrev_b32_e32 v34, 16, v34
	s_waitcnt vmcnt(5)
	v_add_f32_e32 v0, v201, v35
	s_waitcnt vmcnt(4)
	v_add_f32_e32 v2, v202, v34
	s_mov_b32 s44, 0xc1a00000
	ds_write_b32 v93, v0
	v_xor_b32_e32 v0, 0x80000000, v2
	v_cmp_ngt_f32_e32 vcc, s44, v2
	s_and_saveexec_b64 s[60:61], vcc
	s_cbranch_execz .LBB0_239
	v_mul_f32_e32 v0, 0xbfb8aa3b, v2
	v_exp_f32_e32 v0, v0
	s_mov_b32 s44, 0x7f800000
	v_add_f32_e32 v60, 1.0, v0
	v_frexp_mant_f32_e32 v62, v60
	v_cvt_f64_f32_e32 v[2:3], v60
	v_frexp_exp_i32_f64_e32 v2, v[2:3]
	v_cmp_gt_f32_e32 vcc, s64, v62
	v_add_f32_e32 v61, -1.0, v60
	v_sub_f32_e32 v63, v61, v60
	v_subbrev_co_u32_e32 v114, vcc, 0, v2, vcc
	v_sub_u32_e32 v2, 0, v114
	v_sub_f32_e32 v61, v0, v61
	v_add_f32_e32 v63, 1.0, v63
	v_ldexp_f32 v3, v60, v2
	v_add_f32_e32 v61, v61, v63
	v_add_f32_e32 v60, -1.0, v3
	v_add_f32_e32 v62, 1.0, v3
	v_ldexp_f32 v2, v61, v2
	v_add_f32_e32 v61, 1.0, v60
	v_add_f32_e32 v63, -1.0, v62
	v_sub_f32_e32 v61, v3, v61
	v_sub_f32_e32 v3, v3, v63
	v_add_f32_e32 v61, v2, v61
	v_add_f32_e32 v2, v2, v3
	v_add_f32_e32 v115, v62, v2
	v_rcp_f32_e32 v117, v115
	v_sub_f32_e32 v3, v115, v62
	v_sub_f32_e32 v116, v2, v3
	v_add_f32_e32 v3, v60, v61
	v_mul_f32_e32 v119, v3, v117
	v_sub_f32_e32 v2, v3, v60
	v_mul_f32_e32 v60, v115, v119
	v_fma_f32 v62, v119, v115, -v60
	v_fmac_f32_e32 v62, v119, v116
	v_sub_f32_e32 v118, v61, v2
	v_add_f32_e32 v2, v60, v62
	v_sub_f32_e32 v61, v3, v2
	v_pk_add_f32 v[112:113], v[2:3], v[60:61] neg_lo:[0,1] neg_hi:[0,1]
	v_mov_b32_e32 v63, v2
	v_pk_add_f32 v[2:3], v[112:113], v[62:63] neg_lo:[0,1] neg_hi:[0,1]
	v_cmp_neq_f32_e32 vcc, s44, v0
	v_add_f32_e32 v3, v118, v3
	v_add_f32_e32 v2, v2, v3
	v_add_f32_e32 v3, v61, v2
	v_mul_f32_e32 v118, v117, v3
	v_mul_f32_e32 v60, v115, v118
	v_fma_f32 v62, v118, v115, -v60
	v_fmac_f32_e32 v62, v118, v116
	v_sub_f32_e32 v61, v61, v3
	v_add_f32_e32 v115, v2, v61
	v_add_f32_e32 v2, v60, v62
	v_sub_f32_e32 v61, v3, v2
	v_pk_add_f32 v[112:113], v[2:3], v[60:61] neg_lo:[0,1] neg_hi:[0,1]
	v_mov_b32_e32 v63, v2
	v_pk_add_f32 v[2:3], v[112:113], v[62:63] neg_lo:[0,1] neg_hi:[0,1]
	s_mov_b32 s44, 0x33800000
	v_add_f32_e32 v3, v115, v3
	v_add_f32_e32 v2, v2, v3
	v_add_f32_e32 v3, v119, v118
	v_add_f32_e32 v2, v61, v2
	v_sub_f32_e32 v60, v3, v119
	v_mul_f32_e32 v2, v117, v2
	v_sub_f32_e32 v60, v118, v60
	v_add_f32_e32 v60, v60, v2
	v_add_f32_e32 v62, v3, v60
	v_mul_f32_e32 v63, v62, v62
	v_fmamk_f32 v2, v63, 0x3e9b6dac, v162
	v_fmaak_f32 v145, v63, v2, 0x3f2aaada
	v_cvt_f32_i32_e32 v2, v114
	v_sub_f32_e32 v3, v62, v3
	v_sub_f32_e32 v3, v60, v3
	v_ldexp_f32 v112, v3, 1
	v_mul_f32_e32 v3, v62, v63
	v_ldexp_f32 v61, v62, 1
	v_pk_mul_f32 v[62:63], v[2:3], v[144:145]
	s_nop 0
	v_fma_f32 v60, v2, s70, -v62
	v_fmac_f32_e32 v60, 0xb102e308, v2
	v_pk_add_f32 v[2:3], v[62:63], v[60:61]
	s_nop 0
	v_sub_f32_e32 v61, v3, v61
	v_sub_f32_e32 v61, v63, v61
	v_add_f32_e32 v113, v112, v61
	v_mov_b32_e32 v112, v62
	v_pk_add_f32 v[62:63], v[2:3], v[62:63] neg_lo:[0,1] neg_hi:[0,1]
	v_pk_add_f32 v[114:115], v[2:3], v[112:113]
	v_mov_b32_e32 v61, v2
	v_mov_b32_e32 v63, v115
	v_pk_add_f32 v[116:117], v[60:61], v[62:63] neg_lo:[0,1] neg_hi:[0,1]
	v_pk_add_f32 v[60:61], v[60:61], v[62:63]
	v_mov_b32_e32 v112, v113
	v_pk_add_f32 v[62:63], v[60:61], v[2:3] op_sel:[1,0] op_sel_hi:[0,1] neg_lo:[0,1] neg_hi:[0,1]
	v_pk_add_f32 v[118:119], v[114:115], v[62:63] op_sel_hi:[1,0] neg_lo:[0,1] neg_hi:[0,1]
	v_mov_b32_e32 v114, v115
	v_mov_b32_e32 v115, v61
	v_pk_mov_b32 v[62:63], v[2:3], v[62:63] op_sel:[1,0]
	v_mov_b32_e32 v113, v2
	v_pk_add_f32 v[62:63], v[114:115], v[62:63] neg_lo:[0,1] neg_hi:[0,1]
	v_mov_b32_e32 v118, v116
	v_pk_add_f32 v[2:3], v[112:113], v[62:63] neg_lo:[0,1] neg_hi:[0,1]
	v_mov_b32_e32 v117, v61
	v_pk_add_f32 v[62:63], v[118:119], v[2:3]
	s_nop 0
	v_pk_add_f32 v[112:113], v[62:63], v[62:63] op_sel:[0,1] op_sel_hi:[1,0]
	s_nop 0
	v_pk_add_f32 v[60:61], v[60:61], v[112:113] op_sel:[1,0] op_sel_hi:[0,1]
	v_mov_b32_e32 v63, v60
	v_pk_add_f32 v[114:115], v[62:63], v[116:117] neg_lo:[0,1] neg_hi:[0,1]
	v_mov_b32_e32 v3, v112
	v_sub_f32_e32 v61, v62, v114
	v_pk_add_f32 v[2:3], v[2:3], v[114:115] neg_lo:[0,1] neg_hi:[0,1]
	v_sub_f32_e32 v61, v116, v61
	v_add_f32_e32 v2, v2, v61
	v_add_f32_e32 v2, v2, v3
	v_add_f32_e32 v2, v60, v2
	v_cndmask_b32_e32 v2, v172, v2, vcc
	v_cmp_ngt_f32_e32 vcc, -1.0, v0
	s_nop 1
	v_cndmask_b32_e32 v2, v173, v2, vcc
	v_cmp_neq_f32_e32 vcc, -1.0, v0
	s_nop 1
	v_cndmask_b32_e32 v2, v163, v2, vcc
	v_cmp_lt_f32_e64 vcc, |v0|, s44
	s_nop 1
	v_cndmask_b32_e32 v0, v2, v0, vcc
.LBB0_239:
	s_or_b64 exec, exec, s[60:61]
	s_setprio 0
	v_xor_b32_e32 v0, 0x80000000, v0
	ds_write_b32 v122, v0
	s_or_b64 exec, exec, s[46:47]
	s_branch .LBB0_245
